# CIN tile assignment: WGs that run three tiles get q + iq + ik tiles (cheap epilogues); V^T-epilogue tiles go to WGs with two tiles
# speedup vs baseline: 1.0218x; 1.0035x over previous
.LBB0_176:
	s_bfe_u32 s6, s16, 0x20006
	s_xor_b32 s6, s6, 2
	s_add_i32 s6, s6, 4
	s_bfe_u32 s0, s16, 0x30003
	s_lshl_b32 s0, s0, 3
	s_bfe_u32 s1, s16, 0x20003
	s_bfe_u32 s2, s16, 0x30005
	s_lshl_b32 s2, s2, 3
	s_bitcmp1_b32 s16, 8
	s_cselect_b32 s6, s6, s1
	s_cselect_b32 s0, s0, s2
	s_and_b32 s1, s16, 7
	s_add_i32 s0, s0, s1
	s_and_b32 s1, s16, 63
	s_cmpk_lt_u32 s16, 0x200
	s_cselect_b32 s6, s6, 8
	s_cselect_b32 s0, s0, s1
	s_lshl_b32 s2, s0, 8
	s_ashr_i32 s3, s2, 31
	s_ashr_i32 s7, s6, 31
	s_lshl_b64 s[0:1], s[6:7], 19
	s_lshl_b64 s[8:9], s[2:3], 11
	v_readlane_b32 s10, v250, 44
	v_readlane_b32 s11, v250, 45
	s_add_u32 s10, s10, s8
	v_mov_b32_e32 v34, v216
	s_addc_u32 s11, s11, s9
	v_readlane_b32 s3, v252, 33
	s_add_u32 s12, s3, s0
	v_lshlrev_b32_e32 v0, 4, v34
	v_readlane_b32 s3, v252, 34
	v_ashrrev_i32_e32 v35, 3, v34
	v_and_b32_e32 v0, 0x70, v0
	s_addc_u32 s13, s3, s1
	v_lshl_or_b32 v0, v35, 11, v0
	v_lshl_add_u64 v[26:27], s[12:13], 0, v[0:1]
	v_add_co_u32_e32 v10, vcc, s52, v26
	v_lshl_add_u64 v[28:29], s[10:11], 0, v[0:1]
	s_nop 0
	v_addc_co_u32_e32 v11, vcc, 0, v27, vcc
	v_add_co_u32_e32 v14, vcc, s52, v28
	global_load_dwordx4 v[2:5], v0, s[12:13]
	global_load_dwordx4 v[6:9], v0, s[10:11]
	v_addc_co_u32_e32 v15, vcc, 0, v29, vcc
	v_add_co_u32_e32 v18, vcc, s56, v26
	global_load_dwordx4 v[10:13], v[10:11], off
	s_nop 0
	global_load_dwordx4 v[14:17], v[14:15], off
	v_addc_co_u32_e32 v19, vcc, 0, v27, vcc
	v_add_co_u32_e32 v22, vcc, s56, v28
	v_lshrrev_b32_e32 v36, 1, v35
	s_nop 0
	v_addc_co_u32_e32 v23, vcc, 0, v29, vcc
	v_add_co_u32_e32 v26, vcc, s57, v26
	global_load_dwordx4 v[18:21], v[18:19], off
	s_nop 0
	global_load_dwordx4 v[22:25], v[22:23], off
	v_addc_co_u32_e32 v27, vcc, 0, v27, vcc
	v_add_co_u32_e32 v30, vcc, s57, v28
	v_xor_b32_e32 v34, v36, v34
	s_nop 0
	v_addc_co_u32_e32 v31, vcc, 0, v29, vcc
	global_load_dwordx4 v[26:29], v[26:27], off
	s_nop 0
	global_load_dwordx4 v[30:33], v[30:31], off
	v_lshlrev_b32_e32 v35, 7, v35
	v_lshlrev_b32_e32 v34, 4, v34
	v_and_or_b32 v174, v34, s55, v35
	v_add_u32_e32 v175, 0x10000, v174
	s_waitcnt vmcnt(0)
	ds_write_b128 v174, v[2:5]
	s_waitcnt vmcnt(6)
	ds_write_b128 v175, v[6:9]
	s_waitcnt vmcnt(5)
	ds_write_b128 v174, v[10:13] offset:8192
	s_waitcnt vmcnt(4)
	ds_write_b128 v175, v[14:17] offset:8192
	s_waitcnt vmcnt(3)
	ds_write_b128 v174, v[18:21] offset:16384
	s_waitcnt vmcnt(2)
	ds_write_b128 v175, v[22:25] offset:16384
	s_waitcnt vmcnt(1)
	ds_write_b128 v174, v[26:29] offset:24576
	s_waitcnt vmcnt(0)
	ds_write_b128 v175, v[30:33] offset:24576
	s_waitcnt lgkmcnt(0)
	s_barrier
	s_and_saveexec_b64 s[10:11], s[4:5]
	s_cbranch_execz .LBB0_178
	v_add_u32_e32 v2, s2, v216
	v_ashrrev_i32_e32 v3, 31, v2
	v_readlane_b32 s12, v250, 46
	v_lshlrev_b64 v[2:3], 6, v[2:3]
	v_readlane_b32 s13, v250, 47
	s_nop 1
	v_lshl_add_u64 v[14:15], s[12:13], 0, v[2:3]
	global_load_dwordx4 v[2:5], v[14:15], off
	global_load_dwordx4 v[6:9], v[14:15], off offset:16
	global_load_dwordx4 v[10:13], v[14:15], off offset:32
	s_nop 0
	global_load_dwordx4 v[14:17], v[14:15], off offset:48
	s_waitcnt vmcnt(3)
	v_mov_b32_e32 v18, v2
	s_waitcnt vmcnt(2)
	v_mov_b32_e32 v19, v6
	v_mov_b32_e32 v6, v3
	v_mov_b32_e32 v2, v4
	v_mov_b32_e32 v3, v8
	v_mov_b32_e32 v8, v5
	s_waitcnt vmcnt(1)
	v_mov_b32_e32 v4, v10
	s_waitcnt vmcnt(0)
	v_mov_b32_e32 v5, v14
	v_mov_b32_e32 v14, v11
	v_pk_add_f32 v[6:7], v[18:19], v[6:7]
	v_mov_b32_e32 v10, v12
	v_mov_b32_e32 v11, v16
	v_pk_add_f32 v[4:5], v[4:5], v[14:15]
	v_pk_add_f32 v[2:3], v[2:3], v[6:7]
	v_mov_b32_e32 v16, v13
	v_pk_add_f32 v[4:5], v[10:11], v[4:5]
	v_pk_add_f32 v[2:3], v[8:9], v[2:3]
	v_pk_add_f32 v[4:5], v[16:17], v[4:5]
	v_add_f32_e32 v2, v2, v3
	v_add_f32_e32 v2, v2, v4
	v_add_f32_e32 v2, v2, v5
	v_fmamk_f32 v2, v2, 0x3a800000, v206
	v_mul_f32_e32 v3, 0x4b800000, v2
	v_cmp_gt_f32_e32 vcc, s58, v2
	s_nop 1
	v_cndmask_b32_e32 v2, v2, v3, vcc
	v_rsq_f32_e32 v2, v2
	s_nop 0
	v_mul_f32_e32 v3, 0x45800000, v2
	v_cndmask_b32_e32 v2, v2, v3, vcc
	ds_write_b32 v222, v2
